# GLU epilogue prefetch without counted waits: each block drains (vmcnt(0)) and then issues the next block's z loads, so nothing depends on the retirement order of loads vs stores
# speedup vs baseline: 1.0095x; 1.0049x over previous
; __device__ __forceinline__ unsigned cvt_pk_bf16(float lo, float hi) { const f32x2 v = {lo, hi}; return __builtin_bit_cast(unsigned, __builtin_convertvector(v, bf16x2_t)); }
; __device__ __forceinline__ float bf_lo(unsigned w) { return __uint_as_float(w << 16); }
; __device__ __forceinline__ float bf_hi(unsigned w) { return __uint_as_float(w & 0xffff0000u); }
; __device__ __forceinline__ float fast_sigmoid(float v) { return __builtin_amdgcn_rcpf(1.0f + __builtin_amdgcn_exp2f(-1.4426950408889634f * v)); }
; #define ssq2 ((float*)(WSPTR() + WS_SSQ2))
;     __device__ __forceinline__ void operator()(const f32x4 (&acc)[2][2][4][2], const Unit& u, int wr, int wc, int fr, int fq) const {
;         const int row0 = u.pm * BM + wr * 64 + fr;
; #pragma unroll
;         for (int ai = 0; ai < 2; ++ai)
; #pragma unroll
;             for (int m = 0; m < 4; ++m) {
;                 const int row = row0 + ai * HALF + m * 16;
;                 float ss = 0.f;
; #pragma unroll
;                 for (int bj = 0; bj < 2; ++bj) {
;                     const int c0 = u.pn * BM + bj * HALF + wc * 32 + 8 * fq;
;                     const u32x4 zw = *(const u32x4*)(z + (size_t)row * 512 + c0);
;                     const f32x4 b0 = *(const f32x4*)(bglu + c0), b1 = *(const f32x4*)(bglu + c0 + 4);
;                     const f32x4 a0 = acc[ai][bj][m][0] + b0, a1 = acc[ai][bj][m][1] + b1;
;                     float o[8];
;                     o[0] = bf_lo(zw.x) * fast_sigmoid(a0[0]); o[1] = bf_hi(zw.x) * fast_sigmoid(a0[1]);
;                     o[2] = bf_lo(zw.y) * fast_sigmoid(a0[2]); o[3] = bf_hi(zw.y) * fast_sigmoid(a0[3]);
;                     o[4] = bf_lo(zw.z) * fast_sigmoid(a1[0]); o[5] = bf_hi(zw.z) * fast_sigmoid(a1[1]);
;                     o[6] = bf_lo(zw.w) * fast_sigmoid(a1[2]); o[7] = bf_hi(zw.w) * fast_sigmoid(a1[3]);
; #pragma unroll
;                     for (int j = 0; j < 8; ++j) ss += o[j] * o[j];
;                     u32x4 w; w.x = cvt_pk_bf16(o[0], o[1]); w.y = cvt_pk_bf16(o[2], o[3]); w.z = cvt_pk_bf16(o[4], o[5]); w.w = cvt_pk_bf16(o[6], o[7]);
;                     *(u32x4*)(s + (size_t)row * 1024 + 512 + c0) = w;
;                 }
;                 ss += __shfl_xor(ss, 16); ss += __shfl_xor(ss, 32); if (fq == 0) ssq2[((size_t)u.pn * 32768 + row) * 4 + wc] = ss;
.LBB0_590:
	v_lshl_or_b32 v142, s92, 8, v148
	v_ashrrev_i32_e32 v143, 31, v142
	v_lshl_add_u64 v[140:141], v[142:143], 2, s[80:81]
	v_lshl_add_u32 v144, s19, 8, v146
	v_ashrrev_i32_e32 v145, 31, v144
	v_lshlrev_b64 v[158:159], 10, v[144:145]
	v_lshlrev_b64 v[142:143], 1, v[142:143]
	v_lshl_add_u64 v[158:159], s[76:77], 0, v[158:159]
	v_lshl_add_u64 v[178:179], v[158:159], 0, v[142:143]
	v_mov_b64_e32 v[226:227], v[178:179]
	global_load_dwordx4 v[184:187], v[140:141], off
	global_load_dwordx4 v[188:191], v[140:141], off offset:16
	global_load_dwordx4 v[192:195], v[140:141], off offset:512
	global_load_dwordx4 v[196:199], v[140:141], off offset:528
	global_load_dwordx4 v[200:203], v[226:227], off
	global_load_dwordx4 v[204:207], v[226:227], off offset:256
	s_waitcnt vmcnt(0)
	s_mov_b32 s100, 0x4000
	s_mov_b32 s101, 0
	v_lshl_add_u64 v[228:229], v[226:227], 0, s[100:101]
	global_load_dwordx4 v[210:213], v[228:229], off
	global_load_dwordx4 v[214:217], v[228:229], off offset:256
	v_lshlrev_b64 v[180:181], 11, v[144:145]
	v_lshl_add_u64 v[180:181], s[78:79], 0, v[180:181]
	v_lshl_add_u64 v[180:181], v[180:181], 0, v[142:143]
	s_ashr_i32 s93, s92, 31
	s_lshl_b64 s[92:93], s[92:93], 19
	v_mov_b32_e32 v150, v184
	v_mov_b32_e32 v151, v185
	v_mov_b32_e32 v152, v186
	v_mov_b32_e32 v153, v187
	v_mov_b32_e32 v154, v188
	v_mov_b32_e32 v155, v189
	v_mov_b32_e32 v156, v190
	v_mov_b32_e32 v157, v191
	v_mov_b32_e32 v158, v200
	v_mov_b32_e32 v159, v201
	v_mov_b32_e32 v160, v202
	v_mov_b32_e32 v161, v203
	v_pk_add_f32 v[128:129], v[128:129], v[152:153]
	v_pk_add_f32 v[126:127], v[126:127], v[150:151]
	v_pk_add_f32 v[124:125], v[124:125], v[156:157]
	v_pk_add_f32 v[122:123], v[122:123], v[154:155]
	v_mul_f32_e32 v126, 0xbfb8aa3b, v126
	v_mul_f32_e32 v127, 0xbfb8aa3b, v127
	v_mul_f32_e32 v128, 0xbfb8aa3b, v128
	v_mul_f32_e32 v129, 0xbfb8aa3b, v129
	v_mul_f32_e32 v150, 0xbfb8aa3b, v122
	v_mul_f32_e32 v151, 0xbfb8aa3b, v123
	v_mul_f32_e32 v152, 0xbfb8aa3b, v124
	v_mul_f32_e32 v153, 0xbfb8aa3b, v125
	v_exp_f32_e32 v154, v126
	v_exp_f32_e32 v155, v127
	v_exp_f32_e32 v156, v128
	v_exp_f32_e32 v157, v129
	v_exp_f32_e32 v150, v150
	v_exp_f32_e32 v151, v151
	v_exp_f32_e32 v152, v152
	v_exp_f32_e32 v153, v153
	v_lshlrev_b32_e32 v122, 16, v158
	v_and_b32_e32 v123, 0xffff0000, v158
	v_lshlrev_b32_e32 v124, 16, v159
	v_and_b32_e32 v125, 0xffff0000, v159
	v_lshlrev_b32_e32 v126, 16, v160
	v_and_b32_e32 v127, 0xffff0000, v160
	v_lshlrev_b32_e32 v128, 16, v161
	v_and_b32_e32 v129, 0xffff0000, v161
	v_add_f32_e32 v154, 1.0, v154
	v_add_f32_e32 v155, 1.0, v155
	v_add_f32_e32 v156, 1.0, v156
	v_add_f32_e32 v157, 1.0, v157
	v_add_f32_e32 v158, 1.0, v150
	v_add_f32_e32 v159, 1.0, v151
	v_add_f32_e32 v160, 1.0, v152
	v_add_f32_e32 v161, 1.0, v153
	v_rcp_f32_e32 v150, v154
	v_rcp_f32_e32 v151, v155
	v_rcp_f32_e32 v152, v156
	v_rcp_f32_e32 v153, v157
	v_rcp_f32_e32 v154, v158
	v_rcp_f32_e32 v155, v159
	v_rcp_f32_e32 v156, v160
	v_rcp_f32_e32 v157, v161
	v_pk_mul_f32 v[158:159], v[150:151], v[122:123]
	v_pk_mul_f32 v[160:161], v[152:153], v[124:125]
	v_pk_mul_f32 v[182:183], v[154:155], v[126:127]
	v_pk_mul_f32 v[128:129], v[156:157], v[128:129]
	v_cvt_pk_bf16_f32 v122, v158, v159
	v_cvt_pk_bf16_f32 v123, v160, v161
	v_cvt_pk_bf16_f32 v124, v182, v183
	v_cvt_pk_bf16_f32 v125, v128, v129
	global_store_dwordx4 v[180:181], v[122:125], off offset:1024
	s_nop 0
	v_and_b32_e32 v123, 64, v218
	v_xor_b32_e32 v122, 16, v218
	v_add_u32_e32 v123, 64, v123
	v_pk_mul_f32 v[158:159], v[158:159], v[158:159]
	v_xor_b32_e32 v178, 32, v218
	v_cmp_lt_i32_e32 vcc, v122, v123
	v_pk_mul_f32 v[160:161], v[160:161], v[160:161]
	v_add_f32_e32 v158, v158, v159
	v_cndmask_b32_e32 v122, v218, v122, vcc
	v_cmp_lt_i32_e32 vcc, v178, v123
	v_add_f32_e32 v158, v160, v158
	v_add_f32_e32 v158, v161, v158
	v_cndmask_b32_e32 v123, v218, v178, vcc
	v_pk_mul_f32 v[178:179], v[182:183], v[182:183]
	v_pk_mul_f32 v[128:129], v[128:129], v[128:129]
	v_add_f32_e32 v158, v178, v158
	v_add_f32_e32 v158, v179, v158
	v_add_f32_e32 v128, v128, v158
	v_add_f32_e32 v128, v129, v128
	v_lshlrev_b32_e32 v122, 2, v122
	v_mov_b32_e32 v124, v192
	v_mov_b32_e32 v125, v193
	v_mov_b32_e32 v126, v194
	v_mov_b32_e32 v127, v195
	v_mov_b32_e32 v150, v196
	v_mov_b32_e32 v151, v197
	v_mov_b32_e32 v152, v198
	v_mov_b32_e32 v153, v199
	v_mov_b32_e32 v154, v204
	v_mov_b32_e32 v155, v205
	v_mov_b32_e32 v156, v206
	v_mov_b32_e32 v157, v207
	v_pk_add_f32 v[118:119], v[118:119], v[124:125]
	v_pk_add_f32 v[120:121], v[120:121], v[126:127]
	v_pk_add_f32 v[114:115], v[114:115], v[150:151]
	v_mul_f32_e32 v118, 0xbfb8aa3b, v118
	v_mul_f32_e32 v119, 0xbfb8aa3b, v119
	v_pk_add_f32 v[116:117], v[116:117], v[152:153]
	v_mul_f32_e32 v120, 0xbfb8aa3b, v120
	v_mul_f32_e32 v121, 0xbfb8aa3b, v121
	v_mul_f32_e32 v114, 0xbfb8aa3b, v114
	v_mul_f32_e32 v115, 0xbfb8aa3b, v115
	v_exp_f32_e32 v118, v118
	v_exp_f32_e32 v119, v119
	v_mul_f32_e32 v116, 0xbfb8aa3b, v116
	v_mul_f32_e32 v117, 0xbfb8aa3b, v117
	v_exp_f32_e32 v120, v120
	v_exp_f32_e32 v121, v121
	v_exp_f32_e32 v114, v114
	v_exp_f32_e32 v115, v115
	v_exp_f32_e32 v116, v116
	v_exp_f32_e32 v117, v117
	v_add_f32_e32 v118, 1.0, v118
	v_add_f32_e32 v119, 1.0, v119
	v_lshlrev_b32_e32 v124, 16, v154
	v_and_b32_e32 v125, 0xffff0000, v154
	v_lshlrev_b32_e32 v126, 16, v155
	v_and_b32_e32 v127, 0xffff0000, v155
	v_add_f32_e32 v120, 1.0, v120
	v_add_f32_e32 v121, 1.0, v121
	v_add_f32_e32 v154, 1.0, v114
	v_add_f32_e32 v155, 1.0, v115
	v_rcp_f32_e32 v114, v118
	v_rcp_f32_e32 v115, v119
	v_lshlrev_b32_e32 v150, 16, v156
	v_and_b32_e32 v151, 0xffff0000, v156
	v_lshlrev_b32_e32 v152, 16, v157
	v_and_b32_e32 v153, 0xffff0000, v157
	v_add_f32_e32 v156, 1.0, v116
	v_add_f32_e32 v157, 1.0, v117
	v_rcp_f32_e32 v116, v120
	v_rcp_f32_e32 v117, v121
	v_rcp_f32_e32 v118, v154
	v_rcp_f32_e32 v119, v155
	v_pk_mul_f32 v[114:115], v[114:115], v[124:125]
	v_rcp_f32_e32 v120, v156
	v_rcp_f32_e32 v121, v157
	v_pk_mul_f32 v[124:125], v[116:117], v[126:127]
	v_pk_mul_f32 v[116:117], v[114:115], v[114:115]
	v_pk_mul_f32 v[126:127], v[118:119], v[150:151]
	v_add_f32_e32 v116, v116, v128
	v_pk_mul_f32 v[118:119], v[124:125], v[124:125]
	v_add_f32_e32 v116, v117, v116
	v_add_f32_e32 v116, v118, v116
	v_pk_mul_f32 v[150:151], v[120:121], v[152:153]
	v_pk_mul_f32 v[120:121], v[126:127], v[126:127]
	v_add_f32_e32 v116, v119, v116
	v_add_f32_e32 v116, v120, v116
	v_pk_mul_f32 v[152:153], v[150:151], v[150:151]
	v_add_f32_e32 v116, v121, v116
	v_add_f32_e32 v116, v152, v116
	v_add_f32_e32 v117, v153, v116
	ds_bpermute_b32 v119, v122, v117
	v_lshlrev_b32_e32 v116, 2, v123
	v_cvt_pk_bf16_f32 v118, v114, v115
	v_cvt_pk_bf16_f32 v120, v126, v127
	v_cvt_pk_bf16_f32 v121, v150, v151
	s_waitcnt lgkmcnt(0)
	v_add_f32_e32 v114, v117, v119
	ds_bpermute_b32 v115, v116, v114
	v_cvt_pk_bf16_f32 v119, v124, v125
	global_store_dwordx4 v[180:181], v[118:121], off offset:1280
	s_and_saveexec_b64 s[22:23], s[4:5]
	s_cbranch_execz .LBB0_592
; __device__ __forceinline__ unsigned cvt_pk_bf16(float lo, float hi) { const f32x2 v = {lo, hi}; return __builtin_bit_cast(unsigned, __builtin_convertvector(v, bf16x2_t)); }
; __device__ __forceinline__ float bf_lo(unsigned w) { return __uint_as_float(w << 16); }
; __device__ __forceinline__ float bf_hi(unsigned w) { return __uint_as_float(w & 0xffff0000u); }
; __device__ __forceinline__ float fast_sigmoid(float v) { return __builtin_amdgcn_rcpf(1.0f + __builtin_amdgcn_exp2f(-1.4426950408889634f * v)); }
; #define ssq2 ((float*)(WSPTR() + WS_SSQ2))
;     __device__ __forceinline__ void operator()(const f32x4 (&acc)[2][2][4][2], const Unit& u, int wr, int wc, int fr, int fq) const {
;     ...
;                 const int row = row0 + ai * HALF + m * 16;
;                 float ss = 0.f;
; #pragma unroll
;                 for (int bj = 0; bj < 2; ++bj) {
;                     const int c0 = u.pn * BM + bj * HALF + wc * 32 + 8 * fq;
;                     const u32x4 zw = *(const u32x4*)(z + (size_t)row * 512 + c0);
;                     const f32x4 b0 = *(const f32x4*)(bglu + c0), b1 = *(const f32x4*)(bglu + c0 + 4);
;                     const f32x4 a0 = acc[ai][bj][m][0] + b0, a1 = acc[ai][bj][m][1] + b1;
;                     float o[8];
;                     o[0] = bf_lo(zw.x) * fast_sigmoid(a0[0]); o[1] = bf_hi(zw.x) * fast_sigmoid(a0[1]);
;                     o[2] = bf_lo(zw.y) * fast_sigmoid(a0[2]); o[3] = bf_hi(zw.y) * fast_sigmoid(a0[3]);
;                     o[4] = bf_lo(zw.z) * fast_sigmoid(a1[0]); o[5] = bf_hi(zw.z) * fast_sigmoid(a1[1]);
;                     o[6] = bf_lo(zw.w) * fast_sigmoid(a1[2]); o[7] = bf_hi(zw.w) * fast_sigmoid(a1[3]);
; #pragma unroll
;                     for (int j = 0; j < 8; ++j) ss += o[j] * o[j];
;                     u32x4 w; w.x = cvt_pk_bf16(o[0], o[1]); w.y = cvt_pk_bf16(o[2], o[3]); w.z = cvt_pk_bf16(o[4], o[5]); w.w = cvt_pk_bf16(o[6], o[7]);
;                     *(u32x4*)(s + (size_t)row * 1024 + 512 + c0) = w;
;                 }
;                 ss += __shfl_xor(ss, 16); ss += __shfl_xor(ss, 32); if (fq == 0) ssq2[((size_t)u.pn * 32768 + row) * 4 + wc] = ss;
	s_add_u32 s26, s36, s92
	s_addc_u32 s27, s37, s93
	v_lshl_add_u64 v[118:119], v[144:145], 4, s[26:27]
	s_lshl_b32 s52, s38, 2
	v_lshl_add_u64 v[118:119], v[118:119], 0, s[52:53]
	s_waitcnt lgkmcnt(0)
	v_add_f32_e32 v114, v114, v115
	global_store_dword v[118:119], v114, off
.LBB0_592:
	s_or_b64 exec, exec, s[22:23]
	s_waitcnt vmcnt(0)
	s_mov_b32 s100, 0x8000
	s_mov_b32 s101, 0
	v_lshl_add_u64 v[228:229], v[226:227], 0, s[100:101]
	global_load_dwordx4 v[200:203], v[228:229], off
	global_load_dwordx4 v[204:207], v[228:229], off offset:256
	v_or_b32_e32 v114, 16, v144
	s_waitcnt lgkmcnt(0)
	v_ashrrev_i32_e32 v115, 31, v114
	v_lshlrev_b64 v[128:129], 10, v[114:115]
	v_lshl_add_u64 v[128:129], s[76:77], 0, v[128:129]
	v_lshl_add_u64 v[128:129], v[128:129], 0, v[142:143]
	v_lshlrev_b64 v[154:155], 11, v[114:115]
	v_lshl_add_u64 v[154:155], s[78:79], 0, v[154:155]
	v_lshl_add_u64 v[154:155], v[154:155], 0, v[142:143]
	v_mov_b32_e32 v118, v184
	v_mov_b32_e32 v119, v185
	v_mov_b32_e32 v120, v186
	v_mov_b32_e32 v121, v187
	v_mov_b32_e32 v124, v188
	v_mov_b32_e32 v125, v189
	v_mov_b32_e32 v126, v190
	v_mov_b32_e32 v127, v191
	v_mov_b32_e32 v150, v210
	v_mov_b32_e32 v151, v211
	v_mov_b32_e32 v152, v212
	v_mov_b32_e32 v153, v213
	v_pk_add_f32 v[112:113], v[112:113], v[120:121]
	v_pk_add_f32 v[110:111], v[110:111], v[118:119]
	v_pk_add_f32 v[108:109], v[108:109], v[126:127]
	v_pk_add_f32 v[106:107], v[106:107], v[124:125]
	v_mul_f32_e32 v110, 0xbfb8aa3b, v110
	v_mul_f32_e32 v111, 0xbfb8aa3b, v111
	v_mul_f32_e32 v112, 0xbfb8aa3b, v112
	v_mul_f32_e32 v113, 0xbfb8aa3b, v113
	v_mul_f32_e32 v106, 0xbfb8aa3b, v106
	v_mul_f32_e32 v107, 0xbfb8aa3b, v107
	v_mul_f32_e32 v108, 0xbfb8aa3b, v108
	v_mul_f32_e32 v109, 0xbfb8aa3b, v109
	v_exp_f32_e32 v117, v110
	v_exp_f32_e32 v118, v111
	v_exp_f32_e32 v119, v112
	v_exp_f32_e32 v120, v113
	v_exp_f32_e32 v121, v106
	v_exp_f32_e32 v123, v107
	v_exp_f32_e32 v124, v108
	v_exp_f32_e32 v125, v109
	v_lshlrev_b32_e32 v106, 16, v150
	v_and_b32_e32 v107, 0xffff0000, v150
	v_lshlrev_b32_e32 v108, 16, v151
	v_and_b32_e32 v109, 0xffff0000, v151
	v_lshlrev_b32_e32 v110, 16, v152
	v_and_b32_e32 v111, 0xffff0000, v152
	v_add_f32_e32 v117, 1.0, v117
	v_add_f32_e32 v126, 1.0, v118
	v_add_f32_e32 v127, 1.0, v119
	v_add_f32_e32 v145, 1.0, v120
	v_add_f32_e32 v150, 1.0, v121
	v_add_f32_e32 v123, 1.0, v123
	v_add_f32_e32 v151, 1.0, v124
	v_add_f32_e32 v152, 1.0, v125
	v_rcp_f32_e32 v118, v117
	v_rcp_f32_e32 v119, v126
	v_rcp_f32_e32 v120, v127
	v_rcp_f32_e32 v121, v145
	v_rcp_f32_e32 v124, v150
	v_rcp_f32_e32 v125, v123
	v_rcp_f32_e32 v126, v151
	v_rcp_f32_e32 v127, v152
	v_lshlrev_b32_e32 v112, 16, v153
	v_and_b32_e32 v113, 0xffff0000, v153
	v_pk_mul_f32 v[150:151], v[118:119], v[106:107]
	v_pk_mul_f32 v[152:153], v[120:121], v[108:109]
	v_pk_mul_f32 v[124:125], v[124:125], v[110:111]
	v_pk_mul_f32 v[126:127], v[126:127], v[112:113]
	v_cvt_pk_bf16_f32 v106, v150, v151
	v_cvt_pk_bf16_f32 v107, v152, v153
	v_cvt_pk_bf16_f32 v108, v124, v125
	v_cvt_pk_bf16_f32 v109, v126, v127
	global_store_dwordx4 v[154:155], v[106:109], off offset:1024
	s_nop 0
	v_pk_mul_f32 v[128:129], v[150:151], v[150:151]
	v_pk_mul_f32 v[150:151], v[152:153], v[152:153]
	v_add_f32_e32 v117, v128, v129
	v_add_f32_e32 v117, v150, v117
	v_pk_mul_f32 v[124:125], v[124:125], v[124:125]
	v_add_f32_e32 v117, v151, v117
	v_add_f32_e32 v117, v124, v117
	v_pk_mul_f32 v[126:127], v[126:127], v[126:127]
	v_add_f32_e32 v117, v125, v117
	v_add_f32_e32 v117, v126, v117
	v_add_f32_e32 v117, v127, v117
	v_mov_b32_e32 v106, v192
	v_mov_b32_e32 v107, v193
	v_mov_b32_e32 v108, v194
	v_mov_b32_e32 v109, v195
	v_mov_b32_e32 v110, v196
	v_mov_b32_e32 v111, v197
	v_mov_b32_e32 v112, v198
	v_mov_b32_e32 v113, v199
	v_mov_b32_e32 v118, v214
	v_mov_b32_e32 v119, v215
	v_mov_b32_e32 v120, v216
	v_mov_b32_e32 v121, v217
	v_pk_add_f32 v[102:103], v[102:103], v[106:107]
	v_pk_add_f32 v[104:105], v[104:105], v[108:109]
	v_pk_add_f32 v[98:99], v[98:99], v[110:111]
	v_mul_f32_e32 v102, 0xbfb8aa3b, v102
	v_mul_f32_e32 v103, 0xbfb8aa3b, v103
	v_pk_add_f32 v[100:101], v[100:101], v[112:113]
	v_mul_f32_e32 v104, 0xbfb8aa3b, v104
	v_mul_f32_e32 v105, 0xbfb8aa3b, v105
	v_mul_f32_e32 v98, 0xbfb8aa3b, v98
	v_mul_f32_e32 v99, 0xbfb8aa3b, v99
	v_exp_f32_e32 v102, v102
	v_exp_f32_e32 v103, v103
	v_mul_f32_e32 v100, 0xbfb8aa3b, v100
	v_mul_f32_e32 v101, 0xbfb8aa3b, v101
	v_exp_f32_e32 v104, v104
	v_exp_f32_e32 v105, v105
	v_exp_f32_e32 v98, v98
	v_exp_f32_e32 v99, v99
	v_exp_f32_e32 v100, v100
	v_exp_f32_e32 v101, v101
	v_add_f32_e32 v102, 1.0, v102
	v_add_f32_e32 v103, 1.0, v103
	v_lshlrev_b32_e32 v106, 16, v118
	v_and_b32_e32 v107, 0xffff0000, v118
	v_lshlrev_b32_e32 v108, 16, v119
	v_and_b32_e32 v109, 0xffff0000, v119
	v_add_f32_e32 v104, 1.0, v104
	v_add_f32_e32 v105, 1.0, v105
	v_add_f32_e32 v118, 1.0, v98
	v_add_f32_e32 v119, 1.0, v99
	v_rcp_f32_e32 v98, v102
	v_rcp_f32_e32 v99, v103
	v_lshlrev_b32_e32 v110, 16, v120
	v_and_b32_e32 v111, 0xffff0000, v120
	v_lshlrev_b32_e32 v112, 16, v121
	v_and_b32_e32 v113, 0xffff0000, v121
	v_add_f32_e32 v120, 1.0, v100
	v_add_f32_e32 v121, 1.0, v101
	v_rcp_f32_e32 v100, v104
	v_rcp_f32_e32 v101, v105
	v_rcp_f32_e32 v102, v118
	v_rcp_f32_e32 v103, v119
	v_pk_mul_f32 v[98:99], v[98:99], v[106:107]
	v_pk_mul_f32 v[106:107], v[100:101], v[108:109]
	v_pk_mul_f32 v[100:101], v[98:99], v[98:99]
	v_rcp_f32_e32 v104, v120
	v_rcp_f32_e32 v105, v121
	v_add_f32_e32 v100, v100, v117
	v_pk_mul_f32 v[108:109], v[106:107], v[106:107]
	v_add_f32_e32 v100, v101, v100
	v_pk_mul_f32 v[102:103], v[102:103], v[110:111]
	v_add_f32_e32 v100, v108, v100
	v_pk_mul_f32 v[110:111], v[102:103], v[102:103]
	v_add_f32_e32 v100, v109, v100
	v_pk_mul_f32 v[104:105], v[104:105], v[112:113]
	v_add_f32_e32 v100, v110, v100
	v_pk_mul_f32 v[112:113], v[104:105], v[104:105]
	v_add_f32_e32 v100, v111, v100
	v_add_f32_e32 v100, v112, v100
	v_add_f32_e32 v101, v113, v100
	ds_bpermute_b32 v108, v122, v101
	v_cvt_pk_bf16_f32 v100, v98, v99
	v_cvt_pk_bf16_f32 v102, v102, v103
	v_cvt_pk_bf16_f32 v103, v104, v105
	s_waitcnt lgkmcnt(0)
	v_add_f32_e32 v98, v101, v108
	ds_bpermute_b32 v99, v116, v98
	v_cvt_pk_bf16_f32 v101, v106, v107
	global_store_dwordx4 v[154:155], v[100:103], off offset:1280
	s_and_saveexec_b64 s[22:23], s[4:5]
	s_cbranch_execz .LBB0_594
	s_add_u32 s26, s36, s92
	s_addc_u32 s27, s37, s93
	v_lshl_add_u64 v[100:101], v[114:115], 4, s[26:27]
	s_lshl_b32 s52, s38, 2
	v_lshl_add_u64 v[100:101], v[100:101], 0, s[52:53]
	s_waitcnt lgkmcnt(0)
	v_add_f32_e32 v98, v98, v99
	global_store_dword v[100:101], v98, off
; __device__ __forceinline__ unsigned cvt_pk_bf16(float lo, float hi) { const f32x2 v = {lo, hi}; return __builtin_bit_cast(unsigned, __builtin_convertvector(v, bf16x2_t)); }
; __device__ __forceinline__ float bf_lo(unsigned w) { return __uint_as_float(w << 16); }
; __device__ __forceinline__ float bf_hi(unsigned w) { return __uint_as_float(w & 0xffff0000u); }
; __device__ __forceinline__ float fast_sigmoid(float v) { return __builtin_amdgcn_rcpf(1.0f + __builtin_amdgcn_exp2f(-1.4426950408889634f * v)); }
; #define ssq2 ((float*)(WSPTR() + WS_SSQ2))
;     __device__ __forceinline__ void operator()(const f32x4 (&acc)[2][2][4][2], const Unit& u, int wr, int wc, int fr, int fq) const {
;     ...
;                 const int row = row0 + ai * HALF + m * 16;
;                 float ss = 0.f;
; #pragma unroll
;                 for (int bj = 0; bj < 2; ++bj) {
;                     const int c0 = u.pn * BM + bj * HALF + wc * 32 + 8 * fq;
;                     const u32x4 zw = *(const u32x4*)(z + (size_t)row * 512 + c0);
;                     const f32x4 b0 = *(const f32x4*)(bglu + c0), b1 = *(const f32x4*)(bglu + c0 + 4);
;                     const f32x4 a0 = acc[ai][bj][m][0] + b0, a1 = acc[ai][bj][m][1] + b1;
;                     float o[8];
;                     o[0] = bf_lo(zw.x) * fast_sigmoid(a0[0]); o[1] = bf_hi(zw.x) * fast_sigmoid(a0[1]);
;                     o[2] = bf_lo(zw.y) * fast_sigmoid(a0[2]); o[3] = bf_hi(zw.y) * fast_sigmoid(a0[3]);
;                     o[4] = bf_lo(zw.z) * fast_sigmoid(a1[0]); o[5] = bf_hi(zw.z) * fast_sigmoid(a1[1]);
;                     o[6] = bf_lo(zw.w) * fast_sigmoid(a1[2]); o[7] = bf_hi(zw.w) * fast_sigmoid(a1[3]);
; #pragma unroll
;                     for (int j = 0; j < 8; ++j) ss += o[j] * o[j];
;                     u32x4 w; w.x = cvt_pk_bf16(o[0], o[1]); w.y = cvt_pk_bf16(o[2], o[3]); w.z = cvt_pk_bf16(o[4], o[5]); w.w = cvt_pk_bf16(o[6], o[7]);
;                     *(u32x4*)(s + (size_t)row * 1024 + 512 + c0) = w;
;                 }
;                 ss += __shfl_xor(ss, 16); ss += __shfl_xor(ss, 32); if (fq == 0) ssq2[((size_t)u.pn * 32768 + row) * 4 + wc] = ss;
.LBB0_594:
	s_or_b64 exec, exec, s[22:23]
	s_waitcnt vmcnt(0)
	s_mov_b32 s100, 0xc000
	s_mov_b32 s101, 0
	v_lshl_add_u64 v[228:229], v[226:227], 0, s[100:101]
	global_load_dwordx4 v[210:213], v[228:229], off
	global_load_dwordx4 v[214:217], v[228:229], off offset:256
	v_or_b32_e32 v98, 32, v144
	s_waitcnt lgkmcnt(0)
	v_ashrrev_i32_e32 v99, 31, v98
	v_lshlrev_b64 v[108:109], 10, v[98:99]
	v_lshl_add_u64 v[108:109], s[76:77], 0, v[108:109]
	v_lshl_add_u64 v[112:113], v[108:109], 0, v[142:143]
	v_lshlrev_b64 v[114:115], 11, v[98:99]
	v_lshl_add_u64 v[114:115], s[78:79], 0, v[114:115]
	v_lshl_add_u64 v[114:115], v[114:115], 0, v[142:143]
	v_mov_b32_e32 v100, v184
	v_mov_b32_e32 v101, v185
	v_mov_b32_e32 v102, v186
	v_mov_b32_e32 v103, v187
	v_mov_b32_e32 v104, v188
	v_mov_b32_e32 v105, v189
	v_mov_b32_e32 v106, v190
	v_mov_b32_e32 v107, v191
	v_mov_b32_e32 v108, v200
	v_mov_b32_e32 v109, v201
	v_mov_b32_e32 v110, v202
	v_mov_b32_e32 v111, v203
	v_pk_add_f32 v[96:97], v[96:97], v[102:103]
	v_pk_add_f32 v[94:95], v[94:95], v[100:101]
	v_pk_add_f32 v[92:93], v[92:93], v[106:107]
	v_pk_add_f32 v[90:91], v[90:91], v[104:105]
	v_mul_f32_e32 v94, 0xbfb8aa3b, v94
	v_mul_f32_e32 v95, 0xbfb8aa3b, v95
	v_mul_f32_e32 v96, 0xbfb8aa3b, v96
	v_mul_f32_e32 v97, 0xbfb8aa3b, v97
	v_mul_f32_e32 v90, 0xbfb8aa3b, v90
	v_mul_f32_e32 v91, 0xbfb8aa3b, v91
	v_mul_f32_e32 v92, 0xbfb8aa3b, v92
	v_mul_f32_e32 v93, 0xbfb8aa3b, v93
	v_exp_f32_e32 v100, v94
	v_exp_f32_e32 v101, v95
	v_exp_f32_e32 v102, v96
	v_exp_f32_e32 v103, v97
	v_exp_f32_e32 v104, v90
	v_exp_f32_e32 v105, v91
	v_exp_f32_e32 v106, v92
	v_exp_f32_e32 v107, v93
	v_add_f32_e32 v100, 1.0, v100
	v_add_f32_e32 v101, 1.0, v101
	v_add_f32_e32 v102, 1.0, v102
	v_add_f32_e32 v103, 1.0, v103
	v_add_f32_e32 v104, 1.0, v104
	v_add_f32_e32 v105, 1.0, v105
	v_add_f32_e32 v106, 1.0, v106
	v_add_f32_e32 v107, 1.0, v107
	v_rcp_f32_e32 v100, v100
	v_rcp_f32_e32 v101, v101
	v_rcp_f32_e32 v102, v102
	v_rcp_f32_e32 v103, v103
	v_rcp_f32_e32 v104, v104
	v_rcp_f32_e32 v105, v105
	v_rcp_f32_e32 v106, v106
	v_rcp_f32_e32 v107, v107
	v_lshlrev_b32_e32 v90, 16, v108
	v_and_b32_e32 v91, 0xffff0000, v108
	v_lshlrev_b32_e32 v92, 16, v109
	v_and_b32_e32 v93, 0xffff0000, v109
	v_lshlrev_b32_e32 v94, 16, v110
	v_and_b32_e32 v95, 0xffff0000, v110
	v_lshlrev_b32_e32 v96, 16, v111
	v_and_b32_e32 v97, 0xffff0000, v111
	v_pk_mul_f32 v[108:109], v[100:101], v[90:91]
	v_pk_mul_f32 v[110:111], v[102:103], v[92:93]
	v_pk_mul_f32 v[104:105], v[104:105], v[94:95]
	v_pk_mul_f32 v[106:107], v[106:107], v[96:97]
	v_cvt_pk_bf16_f32 v90, v108, v109
	v_cvt_pk_bf16_f32 v91, v110, v111
	v_cvt_pk_bf16_f32 v92, v104, v105
	v_cvt_pk_bf16_f32 v93, v106, v107
	global_store_dwordx4 v[114:115], v[90:93], off offset:1024
	s_nop 0
	v_pk_mul_f32 v[108:109], v[108:109], v[108:109]
	v_pk_mul_f32 v[110:111], v[110:111], v[110:111]
	v_add_f32_e32 v108, v108, v109
	v_add_f32_e32 v108, v110, v108
	v_pk_mul_f32 v[104:105], v[104:105], v[104:105]
	v_add_f32_e32 v108, v111, v108
	v_add_f32_e32 v104, v104, v108
	v_pk_mul_f32 v[106:107], v[106:107], v[106:107]
	v_add_f32_e32 v104, v105, v104
	v_add_f32_e32 v104, v106, v104
	v_mov_b32_e32 v90, v192
	v_mov_b32_e32 v91, v193
	v_mov_b32_e32 v92, v194
	v_mov_b32_e32 v93, v195
	v_mov_b32_e32 v94, v196
	v_mov_b32_e32 v95, v197
	v_mov_b32_e32 v96, v198
	v_mov_b32_e32 v97, v199
	v_mov_b32_e32 v100, v204
	v_mov_b32_e32 v101, v205
	v_mov_b32_e32 v102, v206
	v_mov_b32_e32 v103, v207
	v_pk_add_f32 v[86:87], v[86:87], v[90:91]
	v_pk_add_f32 v[88:89], v[88:89], v[92:93]
	v_pk_add_f32 v[82:83], v[82:83], v[94:95]
	v_mul_f32_e32 v86, 0xbfb8aa3b, v86
	v_mul_f32_e32 v87, 0xbfb8aa3b, v87
	v_pk_add_f32 v[84:85], v[84:85], v[96:97]
	v_mul_f32_e32 v88, 0xbfb8aa3b, v88
	v_mul_f32_e32 v89, 0xbfb8aa3b, v89
	v_mul_f32_e32 v82, 0xbfb8aa3b, v82
	v_mul_f32_e32 v83, 0xbfb8aa3b, v83
	v_exp_f32_e32 v86, v86
	v_exp_f32_e32 v87, v87
	v_mul_f32_e32 v84, 0xbfb8aa3b, v84
	v_mul_f32_e32 v85, 0xbfb8aa3b, v85
	v_exp_f32_e32 v88, v88
	v_exp_f32_e32 v89, v89
	v_exp_f32_e32 v82, v82
	v_exp_f32_e32 v83, v83
	v_exp_f32_e32 v84, v84
	v_exp_f32_e32 v85, v85
	v_add_f32_e32 v86, 1.0, v86
	v_add_f32_e32 v87, 1.0, v87
	v_lshlrev_b32_e32 v90, 16, v100
	v_and_b32_e32 v91, 0xffff0000, v100
	v_lshlrev_b32_e32 v92, 16, v101
	v_and_b32_e32 v93, 0xffff0000, v101
	v_add_f32_e32 v88, 1.0, v88
	v_add_f32_e32 v89, 1.0, v89
	v_add_f32_e32 v100, 1.0, v82
	v_add_f32_e32 v101, 1.0, v83
	v_rcp_f32_e32 v82, v86
	v_rcp_f32_e32 v83, v87
	v_lshlrev_b32_e32 v94, 16, v102
	v_and_b32_e32 v95, 0xffff0000, v102
	v_lshlrev_b32_e32 v96, 16, v103
	v_and_b32_e32 v97, 0xffff0000, v103
	v_add_f32_e32 v102, 1.0, v84
	v_add_f32_e32 v103, 1.0, v85
	v_rcp_f32_e32 v84, v88
	v_rcp_f32_e32 v85, v89
	v_rcp_f32_e32 v86, v100
	v_rcp_f32_e32 v87, v101
	v_pk_mul_f32 v[82:83], v[82:83], v[90:91]
	v_pk_mul_f32 v[90:91], v[84:85], v[92:93]
	v_pk_mul_f32 v[84:85], v[82:83], v[82:83]
	v_add_f32_e32 v100, v107, v104
	v_rcp_f32_e32 v88, v102
	v_rcp_f32_e32 v89, v103
	v_add_f32_e32 v84, v84, v100
	v_pk_mul_f32 v[92:93], v[90:91], v[90:91]
	v_add_f32_e32 v84, v85, v84
	v_pk_mul_f32 v[86:87], v[86:87], v[94:95]
	v_add_f32_e32 v84, v92, v84
	v_pk_mul_f32 v[94:95], v[86:87], v[86:87]
	v_add_f32_e32 v84, v93, v84
	v_pk_mul_f32 v[88:89], v[88:89], v[96:97]
	v_add_f32_e32 v84, v94, v84
	v_pk_mul_f32 v[96:97], v[88:89], v[88:89]
	v_add_f32_e32 v84, v95, v84
	v_add_f32_e32 v84, v96, v84
	v_add_f32_e32 v85, v97, v84
	ds_bpermute_b32 v92, v122, v85
	v_cvt_pk_bf16_f32 v84, v82, v83
	v_cvt_pk_bf16_f32 v86, v86, v87
	v_cvt_pk_bf16_f32 v87, v88, v89
	s_waitcnt lgkmcnt(0)
	v_add_f32_e32 v82, v85, v92
	ds_bpermute_b32 v83, v116, v82
	v_cvt_pk_bf16_f32 v85, v90, v91
	global_store_dwordx4 v[114:115], v[84:87], off offset:1280
	s_and_saveexec_b64 s[22:23], s[4:5]
	s_cbranch_execz .LBB0_596
	s_add_u32 s26, s36, s92
	s_addc_u32 s27, s37, s93
	v_lshl_add_u64 v[84:85], v[98:99], 4, s[26:27]
	s_lshl_b32 s52, s38, 2
	v_lshl_add_u64 v[84:85], v[84:85], 0, s[52:53]
	s_waitcnt lgkmcnt(0)
	v_add_f32_e32 v82, v82, v83
	global_store_dword v[84:85], v82, off
; __device__ __forceinline__ unsigned cvt_pk_bf16(float lo, float hi) { const f32x2 v = {lo, hi}; return __builtin_bit_cast(unsigned, __builtin_convertvector(v, bf16x2_t)); }
; __device__ __forceinline__ float bf_lo(unsigned w) { return __uint_as_float(w << 16); }
; __device__ __forceinline__ float bf_hi(unsigned w) { return __uint_as_float(w & 0xffff0000u); }
; __device__ __forceinline__ float fast_sigmoid(float v) { return __builtin_amdgcn_rcpf(1.0f + __builtin_amdgcn_exp2f(-1.4426950408889634f * v)); }
; #define ssq2 ((float*)(WSPTR() + WS_SSQ2))
;     __device__ __forceinline__ void operator()(const f32x4 (&acc)[2][2][4][2], const Unit& u, int wr, int wc, int fr, int fq) const {
;     ...
;                 const int row = row0 + ai * HALF + m * 16;
;                 float ss = 0.f;
; #pragma unroll
;                 for (int bj = 0; bj < 2; ++bj) {
;                     const int c0 = u.pn * BM + bj * HALF + wc * 32 + 8 * fq;
;                     const u32x4 zw = *(const u32x4*)(z + (size_t)row * 512 + c0);
;                     const f32x4 b0 = *(const f32x4*)(bglu + c0), b1 = *(const f32x4*)(bglu + c0 + 4);
;                     const f32x4 a0 = acc[ai][bj][m][0] + b0, a1 = acc[ai][bj][m][1] + b1;
;                     float o[8];
;                     o[0] = bf_lo(zw.x) * fast_sigmoid(a0[0]); o[1] = bf_hi(zw.x) * fast_sigmoid(a0[1]);
;                     o[2] = bf_lo(zw.y) * fast_sigmoid(a0[2]); o[3] = bf_hi(zw.y) * fast_sigmoid(a0[3]);
;                     o[4] = bf_lo(zw.z) * fast_sigmoid(a1[0]); o[5] = bf_hi(zw.z) * fast_sigmoid(a1[1]);
;                     o[6] = bf_lo(zw.w) * fast_sigmoid(a1[2]); o[7] = bf_hi(zw.w) * fast_sigmoid(a1[3]);
; #pragma unroll
;                     for (int j = 0; j < 8; ++j) ss += o[j] * o[j];
;                     u32x4 w; w.x = cvt_pk_bf16(o[0], o[1]); w.y = cvt_pk_bf16(o[2], o[3]); w.z = cvt_pk_bf16(o[4], o[5]); w.w = cvt_pk_bf16(o[6], o[7]);
;                     *(u32x4*)(s + (size_t)row * 1024 + 512 + c0) = w;
;                 }
;                 ss += __shfl_xor(ss, 16); ss += __shfl_xor(ss, 32); if (fq == 0) ssq2[((size_t)u.pn * 32768 + row) * 4 + wc] = ss;
.LBB0_596:
	s_or_b64 exec, exec, s[22:23]
	s_waitcnt vmcnt(0)
	s_mov_b32 s100, 0x20000
	s_mov_b32 s101, 0
	v_lshl_add_u64 v[228:229], v[226:227], 0, s[100:101]
	global_load_dwordx4 v[200:203], v[228:229], off
	global_load_dwordx4 v[204:207], v[228:229], off offset:256
	v_or_b32_e32 v82, 48, v144
	s_waitcnt lgkmcnt(0)
	v_ashrrev_i32_e32 v83, 31, v82
	v_lshlrev_b64 v[92:93], 10, v[82:83]
	v_lshl_add_u64 v[92:93], s[76:77], 0, v[92:93]
	v_lshl_add_u64 v[96:97], v[92:93], 0, v[142:143]
	v_lshlrev_b64 v[98:99], 11, v[82:83]
	v_lshl_add_u64 v[98:99], s[78:79], 0, v[98:99]
	v_lshl_add_u64 v[98:99], v[98:99], 0, v[142:143]
	v_mov_b32_e32 v84, v184
	v_mov_b32_e32 v85, v185
	v_mov_b32_e32 v86, v186
	v_mov_b32_e32 v87, v187
	v_mov_b32_e32 v88, v188
	v_mov_b32_e32 v89, v189
	v_mov_b32_e32 v90, v190
	v_mov_b32_e32 v91, v191
	v_mov_b32_e32 v92, v210
	v_mov_b32_e32 v93, v211
	v_mov_b32_e32 v94, v212
	v_mov_b32_e32 v95, v213
	v_pk_add_f32 v[80:81], v[80:81], v[86:87]
	v_pk_add_f32 v[78:79], v[78:79], v[84:85]
	v_pk_add_f32 v[76:77], v[76:77], v[90:91]
	v_pk_add_f32 v[74:75], v[74:75], v[88:89]
	v_mul_f32_e32 v78, 0xbfb8aa3b, v78
	v_mul_f32_e32 v79, 0xbfb8aa3b, v79
	v_mul_f32_e32 v80, 0xbfb8aa3b, v80
	v_mul_f32_e32 v81, 0xbfb8aa3b, v81
	v_mul_f32_e32 v74, 0xbfb8aa3b, v74
	v_mul_f32_e32 v75, 0xbfb8aa3b, v75
	v_mul_f32_e32 v76, 0xbfb8aa3b, v76
	v_mul_f32_e32 v77, 0xbfb8aa3b, v77
	v_exp_f32_e32 v84, v78
	v_exp_f32_e32 v85, v79
	v_exp_f32_e32 v86, v80
	v_exp_f32_e32 v87, v81
	v_exp_f32_e32 v88, v74
	v_exp_f32_e32 v89, v75
	v_exp_f32_e32 v90, v76
	v_exp_f32_e32 v91, v77
	v_add_f32_e32 v84, 1.0, v84
	v_add_f32_e32 v85, 1.0, v85
	v_add_f32_e32 v86, 1.0, v86
	v_add_f32_e32 v87, 1.0, v87
	v_add_f32_e32 v88, 1.0, v88
	v_add_f32_e32 v89, 1.0, v89
	v_add_f32_e32 v90, 1.0, v90
	v_add_f32_e32 v91, 1.0, v91
	v_rcp_f32_e32 v84, v84
	v_rcp_f32_e32 v85, v85
	v_rcp_f32_e32 v86, v86
	v_rcp_f32_e32 v87, v87
	v_rcp_f32_e32 v88, v88
	v_rcp_f32_e32 v89, v89
	v_rcp_f32_e32 v90, v90
	v_rcp_f32_e32 v91, v91
	v_lshlrev_b32_e32 v74, 16, v92
	v_and_b32_e32 v75, 0xffff0000, v92
	v_lshlrev_b32_e32 v76, 16, v93
	v_and_b32_e32 v77, 0xffff0000, v93
	v_lshlrev_b32_e32 v78, 16, v94
	v_and_b32_e32 v79, 0xffff0000, v94
	v_lshlrev_b32_e32 v80, 16, v95
	v_and_b32_e32 v81, 0xffff0000, v95
	v_pk_mul_f32 v[92:93], v[84:85], v[74:75]
	v_pk_mul_f32 v[94:95], v[86:87], v[76:77]
	v_pk_mul_f32 v[88:89], v[88:89], v[78:79]
	v_pk_mul_f32 v[90:91], v[90:91], v[80:81]
	v_cvt_pk_bf16_f32 v74, v92, v93
	v_cvt_pk_bf16_f32 v75, v94, v95
	v_cvt_pk_bf16_f32 v76, v88, v89
	v_cvt_pk_bf16_f32 v77, v90, v91
	global_store_dwordx4 v[98:99], v[74:77], off offset:1024
	s_nop 0
	v_pk_mul_f32 v[92:93], v[92:93], v[92:93]
	v_pk_mul_f32 v[94:95], v[94:95], v[94:95]
	v_add_f32_e32 v92, v92, v93
	v_add_f32_e32 v92, v94, v92
	v_pk_mul_f32 v[88:89], v[88:89], v[88:89]
	v_add_f32_e32 v92, v95, v92
	v_add_f32_e32 v88, v88, v92
	v_pk_mul_f32 v[90:91], v[90:91], v[90:91]
	v_add_f32_e32 v88, v89, v88
	v_add_f32_e32 v88, v90, v88
	v_mov_b32_e32 v74, v192
	v_mov_b32_e32 v75, v193
	v_mov_b32_e32 v76, v194
	v_mov_b32_e32 v77, v195
	v_mov_b32_e32 v78, v196
	v_mov_b32_e32 v79, v197
	v_mov_b32_e32 v80, v198
	v_mov_b32_e32 v81, v199
	v_mov_b32_e32 v84, v214
	v_mov_b32_e32 v85, v215
	v_mov_b32_e32 v86, v216
	v_mov_b32_e32 v87, v217
	v_pk_add_f32 v[70:71], v[70:71], v[74:75]
	v_pk_add_f32 v[72:73], v[72:73], v[76:77]
	v_pk_add_f32 v[66:67], v[66:67], v[78:79]
	v_mul_f32_e32 v70, 0xbfb8aa3b, v70
	v_mul_f32_e32 v71, 0xbfb8aa3b, v71
	v_pk_add_f32 v[68:69], v[68:69], v[80:81]
	v_mul_f32_e32 v72, 0xbfb8aa3b, v72
	v_mul_f32_e32 v73, 0xbfb8aa3b, v73
	v_mul_f32_e32 v66, 0xbfb8aa3b, v66
	v_mul_f32_e32 v67, 0xbfb8aa3b, v67
	v_exp_f32_e32 v70, v70
	v_exp_f32_e32 v71, v71
	v_mul_f32_e32 v68, 0xbfb8aa3b, v68
	v_mul_f32_e32 v69, 0xbfb8aa3b, v69
	v_exp_f32_e32 v72, v72
	v_exp_f32_e32 v73, v73
	v_exp_f32_e32 v66, v66
	v_exp_f32_e32 v67, v67
	v_exp_f32_e32 v68, v68
	v_exp_f32_e32 v69, v69
	v_add_f32_e32 v70, 1.0, v70
	v_add_f32_e32 v71, 1.0, v71
	v_lshlrev_b32_e32 v74, 16, v84
	v_and_b32_e32 v75, 0xffff0000, v84
	v_lshlrev_b32_e32 v76, 16, v85
	v_and_b32_e32 v77, 0xffff0000, v85
	v_add_f32_e32 v72, 1.0, v72
	v_add_f32_e32 v73, 1.0, v73
	v_add_f32_e32 v84, 1.0, v66
	v_add_f32_e32 v85, 1.0, v67
	v_rcp_f32_e32 v66, v70
	v_rcp_f32_e32 v67, v71
	v_lshlrev_b32_e32 v78, 16, v86
	v_and_b32_e32 v79, 0xffff0000, v86
	v_lshlrev_b32_e32 v80, 16, v87
	v_and_b32_e32 v81, 0xffff0000, v87
	v_add_f32_e32 v86, 1.0, v68
	v_add_f32_e32 v87, 1.0, v69
	v_rcp_f32_e32 v68, v72
	v_rcp_f32_e32 v69, v73
	v_rcp_f32_e32 v70, v84
	v_rcp_f32_e32 v71, v85
	v_pk_mul_f32 v[66:67], v[66:67], v[74:75]
	v_pk_mul_f32 v[74:75], v[68:69], v[76:77]
	v_pk_mul_f32 v[68:69], v[66:67], v[66:67]
	v_add_f32_e32 v84, v91, v88
	v_rcp_f32_e32 v72, v86
	v_rcp_f32_e32 v73, v87
	v_add_f32_e32 v68, v68, v84
	v_pk_mul_f32 v[76:77], v[74:75], v[74:75]
	v_add_f32_e32 v68, v69, v68
	v_pk_mul_f32 v[70:71], v[70:71], v[78:79]
	v_add_f32_e32 v68, v76, v68
	v_pk_mul_f32 v[78:79], v[70:71], v[70:71]
	v_add_f32_e32 v68, v77, v68
	v_pk_mul_f32 v[72:73], v[72:73], v[80:81]
	v_add_f32_e32 v68, v78, v68
	v_pk_mul_f32 v[80:81], v[72:73], v[72:73]
	v_add_f32_e32 v68, v79, v68
	v_add_f32_e32 v68, v80, v68
	v_add_f32_e32 v69, v81, v68
	ds_bpermute_b32 v76, v122, v69
	v_cvt_pk_bf16_f32 v68, v66, v67
	v_cvt_pk_bf16_f32 v70, v70, v71
	v_cvt_pk_bf16_f32 v71, v72, v73
	s_waitcnt lgkmcnt(0)
	v_add_f32_e32 v66, v69, v76
	ds_bpermute_b32 v67, v116, v66
	v_cvt_pk_bf16_f32 v69, v74, v75
	global_store_dwordx4 v[98:99], v[68:71], off offset:1280
	s_and_saveexec_b64 s[22:23], s[4:5]
	s_cbranch_execz .LBB0_598
	s_add_u32 s26, s36, s92
	s_addc_u32 s27, s37, s93
	v_lshl_add_u64 v[68:69], v[82:83], 4, s[26:27]
	s_lshl_b32 s52, s38, 2
	v_lshl_add_u64 v[68:69], v[68:69], 0, s[52:53]
	s_waitcnt lgkmcnt(0)
	v_add_f32_e32 v66, v66, v67
	global_store_dword v[68:69], v66, off
; __device__ __forceinline__ unsigned cvt_pk_bf16(float lo, float hi) { const f32x2 v = {lo, hi}; return __builtin_bit_cast(unsigned, __builtin_convertvector(v, bf16x2_t)); }
; __device__ __forceinline__ float bf_lo(unsigned w) { return __uint_as_float(w << 16); }
; __device__ __forceinline__ float bf_hi(unsigned w) { return __uint_as_float(w & 0xffff0000u); }
; __device__ __forceinline__ float fast_sigmoid(float v) { return __builtin_amdgcn_rcpf(1.0f + __builtin_amdgcn_exp2f(-1.4426950408889634f * v)); }
; #define ssq2 ((float*)(WSPTR() + WS_SSQ2))
;     __device__ __forceinline__ void operator()(const f32x4 (&acc)[2][2][4][2], const Unit& u, int wr, int wc, int fr, int fq) const {
;     ...
;                 const int row = row0 + ai * HALF + m * 16;
;                 float ss = 0.f;
; #pragma unroll
;                 for (int bj = 0; bj < 2; ++bj) {
;                     const int c0 = u.pn * BM + bj * HALF + wc * 32 + 8 * fq;
;                     const u32x4 zw = *(const u32x4*)(z + (size_t)row * 512 + c0);
;                     const f32x4 b0 = *(const f32x4*)(bglu + c0), b1 = *(const f32x4*)(bglu + c0 + 4);
;                     const f32x4 a0 = acc[ai][bj][m][0] + b0, a1 = acc[ai][bj][m][1] + b1;
;                     float o[8];
;                     o[0] = bf_lo(zw.x) * fast_sigmoid(a0[0]); o[1] = bf_hi(zw.x) * fast_sigmoid(a0[1]);
;                     o[2] = bf_lo(zw.y) * fast_sigmoid(a0[2]); o[3] = bf_hi(zw.y) * fast_sigmoid(a0[3]);
;                     o[4] = bf_lo(zw.z) * fast_sigmoid(a1[0]); o[5] = bf_hi(zw.z) * fast_sigmoid(a1[1]);
;                     o[6] = bf_lo(zw.w) * fast_sigmoid(a1[2]); o[7] = bf_hi(zw.w) * fast_sigmoid(a1[3]);
; #pragma unroll
;                     for (int j = 0; j < 8; ++j) ss += o[j] * o[j];
;                     u32x4 w; w.x = cvt_pk_bf16(o[0], o[1]); w.y = cvt_pk_bf16(o[2], o[3]); w.z = cvt_pk_bf16(o[4], o[5]); w.w = cvt_pk_bf16(o[6], o[7]);
;                     *(u32x4*)(s + (size_t)row * 1024 + 512 + c0) = w;
;                 }
;                 ss += __shfl_xor(ss, 16); ss += __shfl_xor(ss, 32); if (fq == 0) ssq2[((size_t)u.pn * 32768 + row) * 4 + wc] = ss;
.LBB0_598:
	s_or_b64 exec, exec, s[22:23]
	s_waitcnt vmcnt(0)
	s_mov_b32 s100, 0x24000
	s_mov_b32 s101, 0
	v_lshl_add_u64 v[228:229], v[226:227], 0, s[100:101]
	global_load_dwordx4 v[210:213], v[228:229], off
	global_load_dwordx4 v[214:217], v[228:229], off offset:256
	v_add_u32_e32 v66, 0x80, v144
	s_waitcnt lgkmcnt(0)
	v_ashrrev_i32_e32 v67, 31, v66
	v_lshlrev_b64 v[76:77], 10, v[66:67]
	v_lshl_add_u64 v[76:77], s[76:77], 0, v[76:77]
	v_lshl_add_u64 v[80:81], v[76:77], 0, v[142:143]
	v_lshlrev_b64 v[82:83], 11, v[66:67]
	v_lshl_add_u64 v[82:83], s[78:79], 0, v[82:83]
	v_lshl_add_u64 v[82:83], v[82:83], 0, v[142:143]
	v_mov_b32_e32 v68, v184
	v_mov_b32_e32 v69, v185
	v_mov_b32_e32 v70, v186
	v_mov_b32_e32 v71, v187
	v_mov_b32_e32 v72, v188
	v_mov_b32_e32 v73, v189
	v_mov_b32_e32 v74, v190
	v_mov_b32_e32 v75, v191
	v_mov_b32_e32 v76, v200
	v_mov_b32_e32 v77, v201
	v_mov_b32_e32 v78, v202
	v_mov_b32_e32 v79, v203
	v_pk_add_f32 v[64:65], v[64:65], v[70:71]
	v_pk_add_f32 v[62:63], v[62:63], v[68:69]
	v_pk_add_f32 v[60:61], v[60:61], v[74:75]
	v_pk_add_f32 v[58:59], v[58:59], v[72:73]
	v_mul_f32_e32 v62, 0xbfb8aa3b, v62
	v_mul_f32_e32 v63, 0xbfb8aa3b, v63
	v_mul_f32_e32 v64, 0xbfb8aa3b, v64
	v_mul_f32_e32 v65, 0xbfb8aa3b, v65
	v_mul_f32_e32 v58, 0xbfb8aa3b, v58
	v_mul_f32_e32 v59, 0xbfb8aa3b, v59
	v_mul_f32_e32 v60, 0xbfb8aa3b, v60
	v_mul_f32_e32 v61, 0xbfb8aa3b, v61
	v_exp_f32_e32 v68, v62
	v_exp_f32_e32 v69, v63
	v_exp_f32_e32 v70, v64
	v_exp_f32_e32 v71, v65
	v_exp_f32_e32 v72, v58
	v_exp_f32_e32 v73, v59
	v_exp_f32_e32 v74, v60
	v_exp_f32_e32 v75, v61
	v_add_f32_e32 v68, 1.0, v68
	v_add_f32_e32 v69, 1.0, v69
	v_add_f32_e32 v70, 1.0, v70
	v_add_f32_e32 v71, 1.0, v71
	v_add_f32_e32 v72, 1.0, v72
	v_add_f32_e32 v73, 1.0, v73
	v_add_f32_e32 v74, 1.0, v74
	v_add_f32_e32 v75, 1.0, v75
	v_rcp_f32_e32 v68, v68
	v_rcp_f32_e32 v69, v69
	v_rcp_f32_e32 v70, v70
	v_rcp_f32_e32 v71, v71
	v_rcp_f32_e32 v72, v72
	v_rcp_f32_e32 v73, v73
	v_rcp_f32_e32 v74, v74
	v_rcp_f32_e32 v75, v75
	v_lshlrev_b32_e32 v58, 16, v76
	v_and_b32_e32 v59, 0xffff0000, v76
	v_lshlrev_b32_e32 v60, 16, v77
	v_and_b32_e32 v61, 0xffff0000, v77
	v_lshlrev_b32_e32 v62, 16, v78
	v_and_b32_e32 v63, 0xffff0000, v78
	v_lshlrev_b32_e32 v64, 16, v79
	v_and_b32_e32 v65, 0xffff0000, v79
	v_pk_mul_f32 v[76:77], v[68:69], v[58:59]
	v_pk_mul_f32 v[78:79], v[70:71], v[60:61]
	v_pk_mul_f32 v[72:73], v[72:73], v[62:63]
	v_pk_mul_f32 v[74:75], v[74:75], v[64:65]
	v_cvt_pk_bf16_f32 v58, v76, v77
	v_cvt_pk_bf16_f32 v59, v78, v79
	v_cvt_pk_bf16_f32 v60, v72, v73
	v_cvt_pk_bf16_f32 v61, v74, v75
	global_store_dwordx4 v[82:83], v[58:61], off offset:1024
	s_nop 0
	v_pk_mul_f32 v[76:77], v[76:77], v[76:77]
	v_pk_mul_f32 v[78:79], v[78:79], v[78:79]
	v_add_f32_e32 v76, v76, v77
	v_add_f32_e32 v76, v78, v76
	v_pk_mul_f32 v[72:73], v[72:73], v[72:73]
	v_add_f32_e32 v76, v79, v76
	v_add_f32_e32 v72, v72, v76
	v_pk_mul_f32 v[74:75], v[74:75], v[74:75]
	v_add_f32_e32 v72, v73, v72
	v_add_f32_e32 v72, v74, v72
	v_mov_b32_e32 v58, v192
	v_mov_b32_e32 v59, v193
	v_mov_b32_e32 v60, v194
	v_mov_b32_e32 v61, v195
	v_mov_b32_e32 v62, v196
	v_mov_b32_e32 v63, v197
	v_mov_b32_e32 v64, v198
	v_mov_b32_e32 v65, v199
	v_mov_b32_e32 v68, v204
	v_mov_b32_e32 v69, v205
	v_mov_b32_e32 v70, v206
	v_mov_b32_e32 v71, v207
	v_pk_add_f32 v[54:55], v[54:55], v[58:59]
	v_pk_add_f32 v[56:57], v[56:57], v[60:61]
	v_pk_add_f32 v[50:51], v[50:51], v[62:63]
	v_mul_f32_e32 v54, 0xbfb8aa3b, v54
	v_mul_f32_e32 v55, 0xbfb8aa3b, v55
	v_pk_add_f32 v[52:53], v[52:53], v[64:65]
	v_mul_f32_e32 v56, 0xbfb8aa3b, v56
	v_mul_f32_e32 v57, 0xbfb8aa3b, v57
	v_mul_f32_e32 v50, 0xbfb8aa3b, v50
	v_mul_f32_e32 v51, 0xbfb8aa3b, v51
	v_exp_f32_e32 v54, v54
	v_exp_f32_e32 v55, v55
	v_mul_f32_e32 v52, 0xbfb8aa3b, v52
	v_mul_f32_e32 v53, 0xbfb8aa3b, v53
	v_exp_f32_e32 v56, v56
	v_exp_f32_e32 v57, v57
	v_exp_f32_e32 v50, v50
	v_exp_f32_e32 v51, v51
	v_exp_f32_e32 v52, v52
	v_exp_f32_e32 v53, v53
	v_add_f32_e32 v54, 1.0, v54
	v_add_f32_e32 v55, 1.0, v55
	v_lshlrev_b32_e32 v58, 16, v68
	v_and_b32_e32 v59, 0xffff0000, v68
	v_lshlrev_b32_e32 v60, 16, v69
	v_and_b32_e32 v61, 0xffff0000, v69
	v_add_f32_e32 v56, 1.0, v56
	v_add_f32_e32 v57, 1.0, v57
	v_add_f32_e32 v68, 1.0, v50
	v_add_f32_e32 v69, 1.0, v51
	v_rcp_f32_e32 v50, v54
	v_rcp_f32_e32 v51, v55
	v_lshlrev_b32_e32 v62, 16, v70
	v_and_b32_e32 v63, 0xffff0000, v70
	v_lshlrev_b32_e32 v64, 16, v71
	v_and_b32_e32 v65, 0xffff0000, v71
	v_add_f32_e32 v70, 1.0, v52
	v_add_f32_e32 v71, 1.0, v53
	v_rcp_f32_e32 v52, v56
	v_rcp_f32_e32 v53, v57
	v_rcp_f32_e32 v54, v68
	v_rcp_f32_e32 v55, v69
	v_pk_mul_f32 v[50:51], v[50:51], v[58:59]
	v_pk_mul_f32 v[58:59], v[52:53], v[60:61]
	v_pk_mul_f32 v[52:53], v[50:51], v[50:51]
	v_add_f32_e32 v68, v75, v72
	v_rcp_f32_e32 v56, v70
	v_rcp_f32_e32 v57, v71
	v_add_f32_e32 v52, v52, v68
	v_pk_mul_f32 v[60:61], v[58:59], v[58:59]
	v_add_f32_e32 v52, v53, v52
	v_pk_mul_f32 v[54:55], v[54:55], v[62:63]
	v_add_f32_e32 v52, v60, v52
	v_pk_mul_f32 v[62:63], v[54:55], v[54:55]
	v_add_f32_e32 v52, v61, v52
	v_pk_mul_f32 v[56:57], v[56:57], v[64:65]
	v_add_f32_e32 v52, v62, v52
	v_pk_mul_f32 v[64:65], v[56:57], v[56:57]
	v_add_f32_e32 v52, v63, v52
	v_add_f32_e32 v52, v64, v52
	v_add_f32_e32 v53, v65, v52
	ds_bpermute_b32 v60, v122, v53
	v_cvt_pk_bf16_f32 v52, v50, v51
	v_cvt_pk_bf16_f32 v54, v54, v55
	v_cvt_pk_bf16_f32 v55, v56, v57
	s_waitcnt lgkmcnt(0)
	v_add_f32_e32 v50, v53, v60
	ds_bpermute_b32 v51, v116, v50
	v_cvt_pk_bf16_f32 v53, v58, v59
	global_store_dwordx4 v[82:83], v[52:55], off offset:1280
	s_and_saveexec_b64 s[22:23], s[4:5]
	s_cbranch_execz .LBB0_600
	s_add_u32 s26, s36, s92
	s_addc_u32 s27, s37, s93
	v_lshl_add_u64 v[52:53], v[66:67], 4, s[26:27]
	s_lshl_b32 s52, s38, 2
	v_lshl_add_u64 v[52:53], v[52:53], 0, s[52:53]
	s_waitcnt lgkmcnt(0)
	v_add_f32_e32 v50, v50, v51
	global_store_dword v[52:53], v50, off
; __device__ __forceinline__ unsigned cvt_pk_bf16(float lo, float hi) { const f32x2 v = {lo, hi}; return __builtin_bit_cast(unsigned, __builtin_convertvector(v, bf16x2_t)); }
; __device__ __forceinline__ float bf_lo(unsigned w) { return __uint_as_float(w << 16); }
; __device__ __forceinline__ float bf_hi(unsigned w) { return __uint_as_float(w & 0xffff0000u); }
; __device__ __forceinline__ float fast_sigmoid(float v) { return __builtin_amdgcn_rcpf(1.0f + __builtin_amdgcn_exp2f(-1.4426950408889634f * v)); }
; #define ssq2 ((float*)(WSPTR() + WS_SSQ2))
;     __device__ __forceinline__ void operator()(const f32x4 (&acc)[2][2][4][2], const Unit& u, int wr, int wc, int fr, int fq) const {
;     ...
;                 const int row = row0 + ai * HALF + m * 16;
;                 float ss = 0.f;
; #pragma unroll
;                 for (int bj = 0; bj < 2; ++bj) {
;                     const int c0 = u.pn * BM + bj * HALF + wc * 32 + 8 * fq;
;                     const u32x4 zw = *(const u32x4*)(z + (size_t)row * 512 + c0);
;                     const f32x4 b0 = *(const f32x4*)(bglu + c0), b1 = *(const f32x4*)(bglu + c0 + 4);
;                     const f32x4 a0 = acc[ai][bj][m][0] + b0, a1 = acc[ai][bj][m][1] + b1;
;                     float o[8];
;                     o[0] = bf_lo(zw.x) * fast_sigmoid(a0[0]); o[1] = bf_hi(zw.x) * fast_sigmoid(a0[1]);
;                     o[2] = bf_lo(zw.y) * fast_sigmoid(a0[2]); o[3] = bf_hi(zw.y) * fast_sigmoid(a0[3]);
;                     o[4] = bf_lo(zw.z) * fast_sigmoid(a1[0]); o[5] = bf_hi(zw.z) * fast_sigmoid(a1[1]);
;                     o[6] = bf_lo(zw.w) * fast_sigmoid(a1[2]); o[7] = bf_hi(zw.w) * fast_sigmoid(a1[3]);
; #pragma unroll
;                     for (int j = 0; j < 8; ++j) ss += o[j] * o[j];
;                     u32x4 w; w.x = cvt_pk_bf16(o[0], o[1]); w.y = cvt_pk_bf16(o[2], o[3]); w.z = cvt_pk_bf16(o[4], o[5]); w.w = cvt_pk_bf16(o[6], o[7]);
;                     *(u32x4*)(s + (size_t)row * 1024 + 512 + c0) = w;
;                 }
;                 ss += __shfl_xor(ss, 16); ss += __shfl_xor(ss, 32); if (fq == 0) ssq2[((size_t)u.pn * 32768 + row) * 4 + wc] = ss;
.LBB0_600:
	s_or_b64 exec, exec, s[22:23]
	s_waitcnt vmcnt(0)
	s_mov_b32 s100, 0x28000
	s_mov_b32 s101, 0
	v_lshl_add_u64 v[228:229], v[226:227], 0, s[100:101]
	global_load_dwordx4 v[200:203], v[228:229], off
	global_load_dwordx4 v[204:207], v[228:229], off offset:256
	v_add_u32_e32 v50, 0x90, v144
	s_waitcnt lgkmcnt(0)
	v_ashrrev_i32_e32 v51, 31, v50
	v_lshlrev_b64 v[60:61], 10, v[50:51]
	v_lshl_add_u64 v[60:61], s[76:77], 0, v[60:61]
	v_lshl_add_u64 v[64:65], v[60:61], 0, v[142:143]
	v_lshlrev_b64 v[66:67], 11, v[50:51]
	v_lshl_add_u64 v[66:67], s[78:79], 0, v[66:67]
	v_lshl_add_u64 v[66:67], v[66:67], 0, v[142:143]
	v_mov_b32_e32 v52, v184
	v_mov_b32_e32 v53, v185
	v_mov_b32_e32 v54, v186
	v_mov_b32_e32 v55, v187
	v_mov_b32_e32 v56, v188
	v_mov_b32_e32 v57, v189
	v_mov_b32_e32 v58, v190
	v_mov_b32_e32 v59, v191
	v_mov_b32_e32 v60, v210
	v_mov_b32_e32 v61, v211
	v_mov_b32_e32 v62, v212
	v_mov_b32_e32 v63, v213
	v_pk_add_f32 v[48:49], v[48:49], v[54:55]
	v_pk_add_f32 v[46:47], v[46:47], v[52:53]
	v_pk_add_f32 v[44:45], v[44:45], v[58:59]
	v_pk_add_f32 v[42:43], v[42:43], v[56:57]
	v_mul_f32_e32 v46, 0xbfb8aa3b, v46
	v_mul_f32_e32 v47, 0xbfb8aa3b, v47
	v_mul_f32_e32 v48, 0xbfb8aa3b, v48
	v_mul_f32_e32 v49, 0xbfb8aa3b, v49
	v_mul_f32_e32 v42, 0xbfb8aa3b, v42
	v_mul_f32_e32 v43, 0xbfb8aa3b, v43
	v_mul_f32_e32 v44, 0xbfb8aa3b, v44
	v_mul_f32_e32 v45, 0xbfb8aa3b, v45
	v_exp_f32_e32 v52, v46
	v_exp_f32_e32 v53, v47
	v_exp_f32_e32 v54, v48
	v_exp_f32_e32 v55, v49
	v_exp_f32_e32 v56, v42
	v_exp_f32_e32 v57, v43
	v_exp_f32_e32 v58, v44
	v_exp_f32_e32 v59, v45
	v_add_f32_e32 v52, 1.0, v52
	v_add_f32_e32 v53, 1.0, v53
	v_add_f32_e32 v54, 1.0, v54
	v_add_f32_e32 v55, 1.0, v55
	v_add_f32_e32 v56, 1.0, v56
	v_add_f32_e32 v57, 1.0, v57
	v_add_f32_e32 v58, 1.0, v58
	v_add_f32_e32 v59, 1.0, v59
	v_rcp_f32_e32 v52, v52
	v_rcp_f32_e32 v53, v53
	v_rcp_f32_e32 v54, v54
	v_rcp_f32_e32 v55, v55
	v_rcp_f32_e32 v56, v56
	v_rcp_f32_e32 v57, v57
	v_rcp_f32_e32 v58, v58
	v_rcp_f32_e32 v59, v59
	v_lshlrev_b32_e32 v42, 16, v60
	v_and_b32_e32 v43, 0xffff0000, v60
	v_lshlrev_b32_e32 v44, 16, v61
	v_and_b32_e32 v45, 0xffff0000, v61
	v_lshlrev_b32_e32 v46, 16, v62
	v_and_b32_e32 v47, 0xffff0000, v62
	v_lshlrev_b32_e32 v48, 16, v63
	v_and_b32_e32 v49, 0xffff0000, v63
	v_pk_mul_f32 v[60:61], v[52:53], v[42:43]
	v_pk_mul_f32 v[62:63], v[54:55], v[44:45]
	v_pk_mul_f32 v[56:57], v[56:57], v[46:47]
	v_pk_mul_f32 v[58:59], v[58:59], v[48:49]
	v_cvt_pk_bf16_f32 v42, v60, v61
	v_cvt_pk_bf16_f32 v43, v62, v63
	v_cvt_pk_bf16_f32 v44, v56, v57
	v_cvt_pk_bf16_f32 v45, v58, v59
	global_store_dwordx4 v[66:67], v[42:45], off offset:1024
	s_nop 0
	v_pk_mul_f32 v[60:61], v[60:61], v[60:61]
	v_pk_mul_f32 v[62:63], v[62:63], v[62:63]
	v_add_f32_e32 v60, v60, v61
	v_add_f32_e32 v60, v62, v60
	v_pk_mul_f32 v[56:57], v[56:57], v[56:57]
	v_add_f32_e32 v60, v63, v60
	v_add_f32_e32 v56, v56, v60
	v_pk_mul_f32 v[58:59], v[58:59], v[58:59]
	v_add_f32_e32 v56, v57, v56
	v_add_f32_e32 v56, v58, v56
	v_mov_b32_e32 v42, v192
	v_mov_b32_e32 v43, v193
	v_mov_b32_e32 v44, v194
	v_mov_b32_e32 v45, v195
	v_mov_b32_e32 v46, v196
	v_mov_b32_e32 v47, v197
	v_mov_b32_e32 v48, v198
	v_mov_b32_e32 v49, v199
	v_mov_b32_e32 v52, v214
	v_mov_b32_e32 v53, v215
	v_mov_b32_e32 v54, v216
	v_mov_b32_e32 v55, v217
	v_pk_add_f32 v[38:39], v[38:39], v[42:43]
	v_pk_add_f32 v[40:41], v[40:41], v[44:45]
	v_pk_add_f32 v[34:35], v[34:35], v[46:47]
	v_mul_f32_e32 v38, 0xbfb8aa3b, v38
	v_mul_f32_e32 v39, 0xbfb8aa3b, v39
	v_pk_add_f32 v[36:37], v[36:37], v[48:49]
	v_mul_f32_e32 v40, 0xbfb8aa3b, v40
	v_mul_f32_e32 v41, 0xbfb8aa3b, v41
	v_mul_f32_e32 v34, 0xbfb8aa3b, v34
	v_mul_f32_e32 v35, 0xbfb8aa3b, v35
	v_exp_f32_e32 v38, v38
	v_exp_f32_e32 v39, v39
	v_mul_f32_e32 v36, 0xbfb8aa3b, v36
	v_mul_f32_e32 v37, 0xbfb8aa3b, v37
	v_exp_f32_e32 v40, v40
	v_exp_f32_e32 v41, v41
	v_exp_f32_e32 v34, v34
	v_exp_f32_e32 v35, v35
	v_exp_f32_e32 v36, v36
	v_exp_f32_e32 v37, v37
	v_add_f32_e32 v38, 1.0, v38
	v_add_f32_e32 v39, 1.0, v39
	v_lshlrev_b32_e32 v42, 16, v52
	v_and_b32_e32 v43, 0xffff0000, v52
	v_lshlrev_b32_e32 v44, 16, v53
	v_and_b32_e32 v45, 0xffff0000, v53
	v_add_f32_e32 v40, 1.0, v40
	v_add_f32_e32 v41, 1.0, v41
	v_add_f32_e32 v52, 1.0, v34
	v_add_f32_e32 v53, 1.0, v35
	v_rcp_f32_e32 v34, v38
	v_rcp_f32_e32 v35, v39
	v_lshlrev_b32_e32 v46, 16, v54
	v_and_b32_e32 v47, 0xffff0000, v54
	v_lshlrev_b32_e32 v48, 16, v55
	v_and_b32_e32 v49, 0xffff0000, v55
	v_add_f32_e32 v54, 1.0, v36
	v_add_f32_e32 v55, 1.0, v37
	v_rcp_f32_e32 v36, v40
	v_rcp_f32_e32 v37, v41
	v_rcp_f32_e32 v38, v52
	v_rcp_f32_e32 v39, v53
	v_pk_mul_f32 v[34:35], v[34:35], v[42:43]
	v_pk_mul_f32 v[42:43], v[36:37], v[44:45]
	v_pk_mul_f32 v[36:37], v[34:35], v[34:35]
	v_add_f32_e32 v52, v59, v56
	v_rcp_f32_e32 v40, v54
	v_rcp_f32_e32 v41, v55
	v_add_f32_e32 v36, v36, v52
	v_pk_mul_f32 v[44:45], v[42:43], v[42:43]
	v_add_f32_e32 v36, v37, v36
	v_pk_mul_f32 v[38:39], v[38:39], v[46:47]
	v_add_f32_e32 v36, v44, v36
	v_pk_mul_f32 v[46:47], v[38:39], v[38:39]
	v_add_f32_e32 v36, v45, v36
	v_pk_mul_f32 v[40:41], v[40:41], v[48:49]
	v_add_f32_e32 v36, v46, v36
	v_pk_mul_f32 v[48:49], v[40:41], v[40:41]
	v_add_f32_e32 v36, v47, v36
	v_add_f32_e32 v36, v48, v36
	v_add_f32_e32 v37, v49, v36
	ds_bpermute_b32 v44, v122, v37
	v_cvt_pk_bf16_f32 v36, v34, v35
	v_cvt_pk_bf16_f32 v38, v38, v39
	v_cvt_pk_bf16_f32 v39, v40, v41
	s_waitcnt lgkmcnt(0)
	v_add_f32_e32 v34, v37, v44
	ds_bpermute_b32 v35, v116, v34
	v_cvt_pk_bf16_f32 v37, v42, v43
	global_store_dwordx4 v[66:67], v[36:39], off offset:1280
	s_and_saveexec_b64 s[22:23], s[4:5]
	s_cbranch_execz .LBB0_602
	s_add_u32 s26, s36, s92
	s_addc_u32 s27, s37, s93
	v_lshl_add_u64 v[36:37], v[50:51], 4, s[26:27]
	s_lshl_b32 s52, s38, 2
	v_lshl_add_u64 v[36:37], v[36:37], 0, s[52:53]
	s_waitcnt lgkmcnt(0)
	v_add_f32_e32 v34, v34, v35
	global_store_dword v[36:37], v34, off
; __device__ __forceinline__ unsigned cvt_pk_bf16(float lo, float hi) { const f32x2 v = {lo, hi}; return __builtin_bit_cast(unsigned, __builtin_convertvector(v, bf16x2_t)); }
; __device__ __forceinline__ float bf_lo(unsigned w) { return __uint_as_float(w << 16); }
; __device__ __forceinline__ float bf_hi(unsigned w) { return __uint_as_float(w & 0xffff0000u); }
; __device__ __forceinline__ float fast_sigmoid(float v) { return __builtin_amdgcn_rcpf(1.0f + __builtin_amdgcn_exp2f(-1.4426950408889634f * v)); }
; #define ssq2 ((float*)(WSPTR() + WS_SSQ2))
;     __device__ __forceinline__ void operator()(const f32x4 (&acc)[2][2][4][2], const Unit& u, int wr, int wc, int fr, int fq) const {
;     ...
;                 const int row = row0 + ai * HALF + m * 16;
;                 float ss = 0.f;
; #pragma unroll
;                 for (int bj = 0; bj < 2; ++bj) {
;                     const int c0 = u.pn * BM + bj * HALF + wc * 32 + 8 * fq;
;                     const u32x4 zw = *(const u32x4*)(z + (size_t)row * 512 + c0);
;                     const f32x4 b0 = *(const f32x4*)(bglu + c0), b1 = *(const f32x4*)(bglu + c0 + 4);
;                     const f32x4 a0 = acc[ai][bj][m][0] + b0, a1 = acc[ai][bj][m][1] + b1;
;                     float o[8];
;                     o[0] = bf_lo(zw.x) * fast_sigmoid(a0[0]); o[1] = bf_hi(zw.x) * fast_sigmoid(a0[1]);
;                     o[2] = bf_lo(zw.y) * fast_sigmoid(a0[2]); o[3] = bf_hi(zw.y) * fast_sigmoid(a0[3]);
;                     o[4] = bf_lo(zw.z) * fast_sigmoid(a1[0]); o[5] = bf_hi(zw.z) * fast_sigmoid(a1[1]);
;                     o[6] = bf_lo(zw.w) * fast_sigmoid(a1[2]); o[7] = bf_hi(zw.w) * fast_sigmoid(a1[3]);
; #pragma unroll
;                     for (int j = 0; j < 8; ++j) ss += o[j] * o[j];
;                     u32x4 w; w.x = cvt_pk_bf16(o[0], o[1]); w.y = cvt_pk_bf16(o[2], o[3]); w.z = cvt_pk_bf16(o[4], o[5]); w.w = cvt_pk_bf16(o[6], o[7]);
;                     *(u32x4*)(s + (size_t)row * 1024 + 512 + c0) = w;
;                 }
;                 ss += __shfl_xor(ss, 16); ss += __shfl_xor(ss, 32); if (fq == 0) ssq2[((size_t)u.pn * 32768 + row) * 4 + wc] = ss;
.LBB0_602:
	s_or_b64 exec, exec, s[22:23]
	s_waitcnt vmcnt(0)
	s_mov_b32 s100, 0x2c000
	s_mov_b32 s101, 0
	v_lshl_add_u64 v[228:229], v[226:227], 0, s[100:101]
	global_load_dwordx4 v[210:213], v[228:229], off
	global_load_dwordx4 v[214:217], v[228:229], off offset:256
	v_add_u32_e32 v34, 0xa0, v144
	s_waitcnt lgkmcnt(0)
	v_ashrrev_i32_e32 v35, 31, v34
	v_lshlrev_b64 v[44:45], 10, v[34:35]
	v_lshl_add_u64 v[44:45], s[76:77], 0, v[44:45]
	v_lshl_add_u64 v[48:49], v[44:45], 0, v[142:143]
	v_lshlrev_b64 v[50:51], 11, v[34:35]
	v_lshl_add_u64 v[50:51], s[78:79], 0, v[50:51]
	v_lshl_add_u64 v[50:51], v[50:51], 0, v[142:143]
	v_mov_b32_e32 v36, v184
	v_mov_b32_e32 v37, v185
	v_mov_b32_e32 v38, v186
	v_mov_b32_e32 v39, v187
	v_mov_b32_e32 v40, v188
	v_mov_b32_e32 v41, v189
	v_mov_b32_e32 v42, v190
	v_mov_b32_e32 v43, v191
	v_mov_b32_e32 v44, v200
	v_mov_b32_e32 v45, v201
	v_mov_b32_e32 v46, v202
	v_mov_b32_e32 v47, v203
	v_pk_add_f32 v[32:33], v[32:33], v[38:39]
	v_pk_add_f32 v[30:31], v[30:31], v[36:37]
	v_pk_add_f32 v[28:29], v[28:29], v[42:43]
	v_pk_add_f32 v[26:27], v[26:27], v[40:41]
	v_mul_f32_e32 v30, 0xbfb8aa3b, v30
	v_mul_f32_e32 v31, 0xbfb8aa3b, v31
	v_mul_f32_e32 v32, 0xbfb8aa3b, v32
	v_mul_f32_e32 v33, 0xbfb8aa3b, v33
	v_mul_f32_e32 v26, 0xbfb8aa3b, v26
	v_mul_f32_e32 v27, 0xbfb8aa3b, v27
	v_mul_f32_e32 v28, 0xbfb8aa3b, v28
	v_mul_f32_e32 v29, 0xbfb8aa3b, v29
	v_exp_f32_e32 v36, v30
	v_exp_f32_e32 v37, v31
	v_exp_f32_e32 v38, v32
	v_exp_f32_e32 v39, v33
	v_exp_f32_e32 v40, v26
	v_exp_f32_e32 v41, v27
	v_exp_f32_e32 v42, v28
	v_exp_f32_e32 v43, v29
	v_add_f32_e32 v36, 1.0, v36
	v_add_f32_e32 v37, 1.0, v37
	v_add_f32_e32 v38, 1.0, v38
	v_add_f32_e32 v39, 1.0, v39
	v_add_f32_e32 v40, 1.0, v40
	v_add_f32_e32 v41, 1.0, v41
	v_add_f32_e32 v42, 1.0, v42
	v_add_f32_e32 v43, 1.0, v43
	v_rcp_f32_e32 v36, v36
	v_rcp_f32_e32 v37, v37
	v_rcp_f32_e32 v38, v38
	v_rcp_f32_e32 v39, v39
	v_rcp_f32_e32 v40, v40
	v_rcp_f32_e32 v41, v41
	v_rcp_f32_e32 v42, v42
	v_rcp_f32_e32 v43, v43
	v_lshlrev_b32_e32 v26, 16, v44
	v_and_b32_e32 v27, 0xffff0000, v44
	v_lshlrev_b32_e32 v28, 16, v45
	v_and_b32_e32 v29, 0xffff0000, v45
	v_lshlrev_b32_e32 v30, 16, v46
	v_and_b32_e32 v31, 0xffff0000, v46
	v_lshlrev_b32_e32 v32, 16, v47
	v_and_b32_e32 v33, 0xffff0000, v47
	v_pk_mul_f32 v[44:45], v[36:37], v[26:27]
	v_pk_mul_f32 v[46:47], v[38:39], v[28:29]
	v_pk_mul_f32 v[40:41], v[40:41], v[30:31]
	v_pk_mul_f32 v[42:43], v[42:43], v[32:33]
	v_cvt_pk_bf16_f32 v26, v44, v45
	v_cvt_pk_bf16_f32 v27, v46, v47
	v_cvt_pk_bf16_f32 v28, v40, v41
	v_cvt_pk_bf16_f32 v29, v42, v43
	global_store_dwordx4 v[50:51], v[26:29], off offset:1024
	s_nop 0
	v_pk_mul_f32 v[44:45], v[44:45], v[44:45]
	v_pk_mul_f32 v[46:47], v[46:47], v[46:47]
	v_add_f32_e32 v44, v44, v45
	v_add_f32_e32 v44, v46, v44
	v_pk_mul_f32 v[40:41], v[40:41], v[40:41]
	v_add_f32_e32 v44, v47, v44
	v_add_f32_e32 v40, v40, v44
	v_pk_mul_f32 v[42:43], v[42:43], v[42:43]
	v_add_f32_e32 v40, v41, v40
	v_add_f32_e32 v40, v42, v40
	v_mov_b32_e32 v26, v192
	v_mov_b32_e32 v27, v193
	v_mov_b32_e32 v28, v194
	v_mov_b32_e32 v29, v195
	v_mov_b32_e32 v30, v196
	v_mov_b32_e32 v31, v197
	v_mov_b32_e32 v32, v198
	v_mov_b32_e32 v33, v199
	v_mov_b32_e32 v36, v204
	v_mov_b32_e32 v37, v205
	v_mov_b32_e32 v38, v206
	v_mov_b32_e32 v39, v207
	v_pk_add_f32 v[22:23], v[22:23], v[26:27]
	v_pk_add_f32 v[24:25], v[24:25], v[28:29]
	v_pk_add_f32 v[18:19], v[18:19], v[30:31]
	v_mul_f32_e32 v22, 0xbfb8aa3b, v22
	v_mul_f32_e32 v23, 0xbfb8aa3b, v23
	v_pk_add_f32 v[20:21], v[20:21], v[32:33]
	v_mul_f32_e32 v24, 0xbfb8aa3b, v24
	v_mul_f32_e32 v25, 0xbfb8aa3b, v25
	v_mul_f32_e32 v18, 0xbfb8aa3b, v18
	v_mul_f32_e32 v19, 0xbfb8aa3b, v19
	v_exp_f32_e32 v22, v22
	v_exp_f32_e32 v23, v23
	v_mul_f32_e32 v20, 0xbfb8aa3b, v20
	v_mul_f32_e32 v21, 0xbfb8aa3b, v21
	v_exp_f32_e32 v24, v24
	v_exp_f32_e32 v25, v25
	v_exp_f32_e32 v18, v18
	v_exp_f32_e32 v19, v19
	v_exp_f32_e32 v20, v20
	v_exp_f32_e32 v21, v21
	v_add_f32_e32 v22, 1.0, v22
	v_add_f32_e32 v23, 1.0, v23
	v_lshlrev_b32_e32 v26, 16, v36
	v_and_b32_e32 v27, 0xffff0000, v36
	v_lshlrev_b32_e32 v28, 16, v37
	v_and_b32_e32 v29, 0xffff0000, v37
	v_add_f32_e32 v24, 1.0, v24
	v_add_f32_e32 v25, 1.0, v25
	v_add_f32_e32 v36, 1.0, v18
	v_add_f32_e32 v37, 1.0, v19
	v_rcp_f32_e32 v18, v22
	v_rcp_f32_e32 v19, v23
	v_lshlrev_b32_e32 v30, 16, v38
	v_and_b32_e32 v31, 0xffff0000, v38
	v_lshlrev_b32_e32 v32, 16, v39
	v_and_b32_e32 v33, 0xffff0000, v39
	v_add_f32_e32 v38, 1.0, v20
	v_add_f32_e32 v39, 1.0, v21
	v_rcp_f32_e32 v20, v24
	v_rcp_f32_e32 v21, v25
	v_rcp_f32_e32 v22, v36
	v_rcp_f32_e32 v23, v37
	v_pk_mul_f32 v[18:19], v[18:19], v[26:27]
	v_pk_mul_f32 v[26:27], v[20:21], v[28:29]
	v_pk_mul_f32 v[20:21], v[18:19], v[18:19]
	v_add_f32_e32 v36, v43, v40
	v_rcp_f32_e32 v24, v38
	v_rcp_f32_e32 v25, v39
	v_add_f32_e32 v20, v20, v36
	v_pk_mul_f32 v[28:29], v[26:27], v[26:27]
	v_add_f32_e32 v20, v21, v20
	v_pk_mul_f32 v[22:23], v[22:23], v[30:31]
	v_add_f32_e32 v20, v28, v20
	v_pk_mul_f32 v[30:31], v[22:23], v[22:23]
	v_add_f32_e32 v20, v29, v20
	v_pk_mul_f32 v[24:25], v[24:25], v[32:33]
	v_add_f32_e32 v20, v30, v20
	v_pk_mul_f32 v[32:33], v[24:25], v[24:25]
	v_add_f32_e32 v20, v31, v20
	v_add_f32_e32 v20, v32, v20
	v_add_f32_e32 v21, v33, v20
	ds_bpermute_b32 v28, v122, v21
	v_cvt_pk_bf16_f32 v20, v18, v19
	v_cvt_pk_bf16_f32 v22, v22, v23
	v_cvt_pk_bf16_f32 v23, v24, v25
	s_waitcnt lgkmcnt(0)
	v_add_f32_e32 v18, v21, v28
	ds_bpermute_b32 v19, v116, v18
	v_cvt_pk_bf16_f32 v21, v26, v27
	global_store_dwordx4 v[50:51], v[20:23], off offset:1280
	s_and_saveexec_b64 s[22:23], s[4:5]
	s_cbranch_execz .LBB0_604
	s_add_u32 s26, s36, s92
	s_addc_u32 s27, s37, s93
	v_lshl_add_u64 v[20:21], v[34:35], 4, s[26:27]
	s_lshl_b32 s52, s38, 2
	v_lshl_add_u64 v[20:21], v[20:21], 0, s[52:53]
	s_waitcnt lgkmcnt(0)
	v_add_f32_e32 v18, v18, v19
	global_store_dword v[20:21], v18, off
